# final gate GEMM epilogue: the h and p operand requests issued four 16-row steps ahead into a register ring
# baseline (speedup 1.0000x reference)
; __device__ __forceinline__ u32x4 pack8(const f32x4 a, const f32x4 b) { u32x4 w; w.x = cvt_pk_bf16(a[0], a[1]); w.y = cvt_pk_bf16(a[2], a[3]); w.z = cvt_pk_bf16(b[0], b[1]); w.w = cvt_pk_bf16(b[2], b[3]); return w; }
; __device__ __forceinline__ void unpack8(const u32x4 w, f32x4& a, f32x4& b) { a = (f32x4){bflo(w.x), bfhi(w.x), bflo(w.y), bfhi(w.y)}; b = (f32x4){bflo(w.z), bfhi(w.z), bflo(w.w), bfhi(w.w)}; }
; __device__ __forceinline__ float fsigmoid(float x) { return __builtin_amdgcn_rcpf(1.0f + __expf(-x)); }
;     __device__ __forceinline__ void operator()(const f32x4 (&acc)[2][2][4][2], const Unit& u, int wr, int wc, int fr, int fq) const {
;     ...
;             for (int m = 0; m < 4; ++m) { const size_t off = (size_t)(row0 + ai * HALF + m * 16) * 1024 + col0;
; #pragma unroll
;                 for (int bj = 0; bj < 2; ++bj) { f32x4 h0, h1, p0, p1;
;                     unpack8(*(const u32x4*)(hpre + off + bj * HALF), h0, h1); unpack8(*(const u32x4*)(pp + off + bj * HALF), p0, p1);
;                     f32x4 g0, g1;
; #pragma unroll
;                     for (int e = 0; e < 4; ++e) { g0[e] = fsigmoid(acc[ai][bj][m][0][e]); g1[e] = fsigmoid(acc[ai][bj][m][1][e]); }
;                     const f32x4 o0 = h0 + g0 * p0, o1 = h1 + g1 * p1;
;                     if (F32OUT) { *(f32x4*)((float*)O + off + bj * HALF) = o0; *(f32x4*)((float*)O + off + bj * HALF + 4) = o1; }
;                     else *(u32x4*)((bf16_t*)O + off + bj * HALF) = pack8(o0, o1); } }
.LBB0_1178:
	v_lshl_add_u32 v148, s36, 8, v150
	v_lshl_or_b32 v146, s57, 8, v152
	v_ashrrev_i32_e32 v149, 31, v148
	v_ashrrev_i32_e32 v147, 31, v146
	v_lshlrev_b64 v[144:145], 10, v[148:149]
	v_lshl_add_u64 v[144:145], v[144:145], 0, v[146:147]
	v_lshlrev_b64 v[144:145], 1, v[144:145]
	v_lshl_add_u64 v[164:165], s[6:7], 0, v[144:145]
	v_lshl_add_u64 v[166:167], s[12:13], 0, v[144:145]
	v_mov_b64_e32 v[176:177], v[164:165]
	v_mov_b64_e32 v[192:193], v[166:167]
	v_mov_b32_e32 v240, 0x8000
	v_mov_b32_e32 v241, 0
	v_lshl_add_u64 v[178:179], v[240:241], 0, v[176:177]
	v_lshl_add_u64 v[180:181], v[240:241], 1, v[176:177]
	v_lshl_add_u64 v[182:183], v[240:241], 1, v[178:179]
	v_lshl_add_u64 v[184:185], v[240:241], 3, v[176:177]
	v_lshl_add_u64 v[186:187], v[240:241], 0, v[184:185]
	v_lshl_add_u64 v[188:189], v[240:241], 1, v[184:185]
	v_lshl_add_u64 v[190:191], v[240:241], 1, v[186:187]
	v_lshl_add_u64 v[194:195], v[240:241], 0, v[192:193]
	v_lshl_add_u64 v[196:197], v[240:241], 1, v[192:193]
	v_lshl_add_u64 v[198:199], v[240:241], 1, v[194:195]
	v_lshl_add_u64 v[200:201], v[240:241], 3, v[192:193]
	v_lshl_add_u64 v[202:203], v[240:241], 0, v[200:201]
	v_lshl_add_u64 v[204:205], v[240:241], 1, v[200:201]
	v_lshl_add_u64 v[206:207], v[240:241], 1, v[202:203]
	global_load_dwordx4 v[208:211], v[176:177], off
	global_load_dwordx4 v[212:215], v[192:193], off
	global_load_dwordx4 v[216:219], v[176:177], off offset:256
	global_load_dwordx4 v[220:223], v[192:193], off offset:256
	global_load_dwordx4 v[224:227], v[178:179], off
	global_load_dwordx4 v[228:231], v[194:195], off
	global_load_dwordx4 v[232:235], v[178:179], off offset:256
	global_load_dwordx4 v[236:239], v[194:195], off offset:256
	v_mul_f32_e32 v124, 0xbfb8aa3b, v124
	v_mul_f32_e32 v120, 0xbfb8aa3b, v120
	v_mul_f32_e32 v125, 0xbfb8aa3b, v125
	v_mul_f32_e32 v121, 0xbfb8aa3b, v121
	v_mul_f32_e32 v126, 0xbfb8aa3b, v126
	v_mul_f32_e32 v122, 0xbfb8aa3b, v122
	v_mul_f32_e32 v127, 0xbfb8aa3b, v127
	v_mul_f32_e32 v123, 0xbfb8aa3b, v123
	v_exp_f32_e32 v124, v124
	v_exp_f32_e32 v120, v120
	v_exp_f32_e32 v125, v125
	v_exp_f32_e32 v121, v121
	v_exp_f32_e32 v126, v126
	v_exp_f32_e32 v122, v122
	v_exp_f32_e32 v127, v127
	v_exp_f32_e32 v123, v123
	v_add_f32_e32 v124, 1.0, v124
	v_add_f32_e32 v149, 1.0, v120
	v_add_f32_e32 v125, 1.0, v125
	v_add_f32_e32 v168, 1.0, v121
	v_add_f32_e32 v126, 1.0, v126
	v_add_f32_e32 v169, 1.0, v122
	v_add_f32_e32 v127, 1.0, v127
	v_add_f32_e32 v170, 1.0, v123
	v_rcp_f32_e32 v120, v124
	v_rcp_f32_e32 v122, v149
	v_rcp_f32_e32 v121, v125
	v_rcp_f32_e32 v123, v168
	v_rcp_f32_e32 v124, v126
	v_rcp_f32_e32 v126, v169
	v_rcp_f32_e32 v125, v127
	v_rcp_f32_e32 v127, v170
	v_mul_f32_e32 v116, 0xbfb8aa3b, v116
	v_mul_f32_e32 v112, 0xbfb8aa3b, v112
	v_mul_f32_e32 v117, 0xbfb8aa3b, v117
	v_mul_f32_e32 v113, 0xbfb8aa3b, v113
	v_mul_f32_e32 v118, 0xbfb8aa3b, v118
	v_mul_f32_e32 v119, 0xbfb8aa3b, v119
	v_mul_f32_e32 v114, 0xbfb8aa3b, v114
	v_mul_f32_e32 v115, 0xbfb8aa3b, v115
	v_exp_f32_e32 v116, v116
	v_exp_f32_e32 v149, v112
	v_exp_f32_e32 v117, v117
	v_exp_f32_e32 v114, v114
	v_exp_f32_e32 v115, v115
	v_add_f32_e32 v116, 1.0, v116
	v_add_f32_e32 v149, 1.0, v149
	v_add_f32_e32 v117, 1.0, v117
	v_or_b32_e32 v112, 16, v148
	v_mul_f32_e32 v108, 0xbfb8aa3b, v108
	v_mul_f32_e32 v104, 0xbfb8aa3b, v104
	v_mul_f32_e32 v109, 0xbfb8aa3b, v109
	v_mul_f32_e32 v105, 0xbfb8aa3b, v105
	v_mul_f32_e32 v110, 0xbfb8aa3b, v110
	v_mul_f32_e32 v106, 0xbfb8aa3b, v106
	v_mul_f32_e32 v111, 0xbfb8aa3b, v111
	v_mul_f32_e32 v107, 0xbfb8aa3b, v107
	v_exp_f32_e32 v108, v108
	v_exp_f32_e32 v104, v104
	v_exp_f32_e32 v109, v109
	v_exp_f32_e32 v105, v105
	v_exp_f32_e32 v110, v110
	v_exp_f32_e32 v106, v106
	v_exp_f32_e32 v111, v111
	v_exp_f32_e32 v107, v107
	v_add_f32_e32 v108, 1.0, v108
	v_add_f32_e32 v109, 1.0, v109
	v_add_f32_e32 v110, 1.0, v110
	v_add_f32_e32 v111, 1.0, v111
	v_mul_f32_e32 v100, 0xbfb8aa3b, v100
	v_mul_f32_e32 v96, 0xbfb8aa3b, v96
	v_mul_f32_e32 v101, 0xbfb8aa3b, v101
	v_mul_f32_e32 v97, 0xbfb8aa3b, v97
	v_mul_f32_e32 v102, 0xbfb8aa3b, v102
	v_mul_f32_e32 v103, 0xbfb8aa3b, v103
	v_mul_f32_e32 v98, 0xbfb8aa3b, v98
	v_mul_f32_e32 v99, 0xbfb8aa3b, v99
	v_exp_f32_e32 v100, v100
	s_waitcnt vmcnt(6)
	v_lshlrev_b32_e32 v168, 16, v208
	v_and_b32_e32 v169, 0xffff0000, v208
	v_lshlrev_b32_e32 v156, 16, v209
	v_and_b32_e32 v157, 0xffff0000, v209
	v_lshlrev_b32_e32 v170, 16, v210
	v_and_b32_e32 v171, 0xffff0000, v210
	v_lshlrev_b32_e32 v158, 16, v211
	v_and_b32_e32 v159, 0xffff0000, v211
	v_lshlrev_b32_e32 v172, 16, v212
	v_and_b32_e32 v173, 0xffff0000, v212
	v_lshlrev_b32_e32 v160, 16, v213
	v_and_b32_e32 v161, 0xffff0000, v213
	v_lshlrev_b32_e32 v174, 16, v214
	v_and_b32_e32 v175, 0xffff0000, v214
	v_lshlrev_b32_e32 v162, 16, v215
	v_and_b32_e32 v163, 0xffff0000, v215
	v_pk_fma_f32 v[124:125], v[124:125], v[160:161], v[156:157]
	v_pk_fma_f32 v[120:121], v[120:121], v[172:173], v[168:169]
	v_pk_fma_f32 v[126:127], v[126:127], v[162:163], v[158:159]
	v_pk_fma_f32 v[122:123], v[122:123], v[174:175], v[170:171]
	v_cvt_pk_bf16_f32 v120, v120, v121
	v_cvt_pk_bf16_f32 v121, v124, v125
	v_exp_f32_e32 v160, v113
	v_cvt_pk_bf16_f32 v122, v122, v123
	v_cvt_pk_bf16_f32 v123, v126, v127
	v_exp_f32_e32 v161, v118
	v_exp_f32_e32 v162, v119
	v_add_f32_e32 v160, 1.0, v160
	v_add_f32_e32 v163, 1.0, v114
	v_add_f32_e32 v161, 1.0, v161
	v_add_f32_e32 v164, 1.0, v162
	v_add_f32_e32 v165, 1.0, v115
	v_rcp_f32_e32 v114, v116
	v_rcp_f32_e32 v116, v149
	v_rcp_f32_e32 v115, v117
	v_rcp_f32_e32 v117, v160
	v_rcp_f32_e32 v160, v161
	v_rcp_f32_e32 v161, v164
	v_ashrrev_i32_e32 v113, 31, v112
	v_rcp_f32_e32 v162, v163
	v_rcp_f32_e32 v163, v165
; __device__ __forceinline__ float fsigmoid(float x) { return __builtin_amdgcn_rcpf(1.0f + __expf(-x)); }
; __device__ __forceinline__ u32x4 pack8(const f32x4 a, const f32x4 b) { u32x4 w; w.x = cvt_pk_bf16(a[0], a[1]); w.y = cvt_pk_bf16(a[2], a[3]); w.z = cvt_pk_bf16(b[0], b[1]); w.w = cvt_pk_bf16(b[2], b[3]); return w; }
; __device__ __forceinline__ void unpack8(const u32x4 w, f32x4& a, f32x4& b) { a = (f32x4){bflo(w.x), bfhi(w.x), bflo(w.y), bfhi(w.y)}; b = (f32x4){bflo(w.z), bfhi(w.z), bflo(w.w), bfhi(w.w)}; }
;     __device__ __forceinline__ void operator()(const f32x4 (&acc)[2][2][4][2], const Unit& u, int wr, int wc, int fr, int fq) const {
;     ...
;             for (int m = 0; m < 4; ++m) { const size_t off = (size_t)(row0 + ai * HALF + m * 16) * 1024 + col0;
; #pragma unroll
;                 for (int bj = 0; bj < 2; ++bj) { f32x4 h0, h1, p0, p1;
;                     unpack8(*(const u32x4*)(hpre + off + bj * HALF), h0, h1); unpack8(*(const u32x4*)(pp + off + bj * HALF), p0, p1);
;                     f32x4 g0, g1;
; #pragma unroll
;                     for (int e = 0; e < 4; ++e) { g0[e] = fsigmoid(acc[ai][bj][m][0][e]); g1[e] = fsigmoid(acc[ai][bj][m][1][e]); }
;                     const f32x4 o0 = h0 + g0 * p0, o1 = h1 + g1 * p1;
;                     if (F32OUT) { *(f32x4*)((float*)O + off + bj * HALF) = o0; *(f32x4*)((float*)O + off + bj * HALF + 4) = o1; }
;                     else *(u32x4*)((bf16_t*)O + off + bj * HALF) = pack8(o0, o1); } }
	v_lshlrev_b64 v[112:113], 10, v[112:113]
	v_lshl_add_u64 v[118:119], s[14:15], 0, v[144:145]
	v_lshl_add_u64 v[112:113], v[112:113], 0, v[146:147]
	global_store_dwordx4 v[118:119], v[120:123], off
	global_load_dwordx4 v[208:211], v[180:181], off
	global_load_dwordx4 v[212:215], v[196:197], off
	v_lshlrev_b64 v[112:113], 1, v[112:113]
	v_lshl_add_u64 v[164:165], s[6:7], 0, v[112:113]
	v_exp_f32_e32 v101, v101
	v_exp_f32_e32 v102, v102
	v_exp_f32_e32 v103, v103
	v_exp_f32_e32 v98, v98
	v_exp_f32_e32 v99, v99
	v_add_f32_e32 v100, 1.0, v100
	v_add_f32_e32 v101, 1.0, v101
	v_mul_f32_e32 v92, 0xbfb8aa3b, v92
	v_mul_f32_e32 v88, 0xbfb8aa3b, v88
	v_mul_f32_e32 v93, 0xbfb8aa3b, v93
	v_mul_f32_e32 v89, 0xbfb8aa3b, v89
	v_mul_f32_e32 v94, 0xbfb8aa3b, v94
	v_mul_f32_e32 v90, 0xbfb8aa3b, v90
	v_mul_f32_e32 v95, 0xbfb8aa3b, v95
	v_mul_f32_e32 v91, 0xbfb8aa3b, v91
	v_exp_f32_e32 v92, v92
	v_exp_f32_e32 v88, v88
	v_exp_f32_e32 v93, v93
	v_exp_f32_e32 v89, v89
	v_exp_f32_e32 v94, v94
	v_exp_f32_e32 v90, v90
	v_exp_f32_e32 v95, v95
	v_exp_f32_e32 v91, v91
	v_add_f32_e32 v92, 1.0, v92
	v_add_f32_e32 v93, 1.0, v93
	v_add_f32_e32 v94, 1.0, v94
	v_add_f32_e32 v95, 1.0, v95
	v_mul_f32_e32 v84, 0xbfb8aa3b, v84
	v_mul_f32_e32 v80, 0xbfb8aa3b, v80
	v_mul_f32_e32 v85, 0xbfb8aa3b, v85
	v_mul_f32_e32 v81, 0xbfb8aa3b, v81
	v_mul_f32_e32 v86, 0xbfb8aa3b, v86
	v_mul_f32_e32 v87, 0xbfb8aa3b, v87
	v_mul_f32_e32 v82, 0xbfb8aa3b, v82
	v_mul_f32_e32 v83, 0xbfb8aa3b, v83
	v_exp_f32_e32 v84, v84
	v_exp_f32_e32 v85, v85
	v_exp_f32_e32 v86, v86
	v_exp_f32_e32 v87, v87
	v_exp_f32_e32 v82, v82
	v_exp_f32_e32 v83, v83
	v_add_f32_e32 v84, 1.0, v84
	v_add_f32_e32 v85, 1.0, v85
	v_mul_f32_e32 v76, 0xbfb8aa3b, v76
	v_mul_f32_e32 v72, 0xbfb8aa3b, v72
	v_mul_f32_e32 v77, 0xbfb8aa3b, v77
	v_mul_f32_e32 v73, 0xbfb8aa3b, v73
	v_mul_f32_e32 v78, 0xbfb8aa3b, v78
	v_mul_f32_e32 v74, 0xbfb8aa3b, v74
	v_mul_f32_e32 v79, 0xbfb8aa3b, v79
	v_mul_f32_e32 v75, 0xbfb8aa3b, v75
	v_exp_f32_e32 v76, v76
	v_exp_f32_e32 v72, v72
	v_exp_f32_e32 v77, v77
	v_exp_f32_e32 v73, v73
	v_exp_f32_e32 v78, v78
	s_waitcnt vmcnt(7)
	v_lshlrev_b32_e32 v120, 16, v216
	v_and_b32_e32 v121, 0xffff0000, v216
	v_lshlrev_b32_e32 v122, 16, v217
	v_and_b32_e32 v123, 0xffff0000, v217
	v_lshlrev_b32_e32 v124, 16, v218
	v_and_b32_e32 v125, 0xffff0000, v218
	v_lshlrev_b32_e32 v166, 16, v220
	v_and_b32_e32 v167, 0xffff0000, v220
	v_lshlrev_b32_e32 v156, 16, v221
	v_and_b32_e32 v157, 0xffff0000, v221
	v_lshlrev_b32_e32 v168, 16, v222
	v_and_b32_e32 v169, 0xffff0000, v222
	v_lshlrev_b32_e32 v126, 16, v219
	v_and_b32_e32 v127, 0xffff0000, v219
	v_lshlrev_b32_e32 v158, 16, v223
	v_and_b32_e32 v159, 0xffff0000, v223
	v_pk_fma_f32 v[122:123], v[160:161], v[156:157], v[122:123]
	v_pk_fma_f32 v[114:115], v[114:115], v[166:167], v[120:121]
	v_pk_fma_f32 v[116:117], v[116:117], v[168:169], v[124:125]
	v_pk_fma_f32 v[120:121], v[162:163], v[158:159], v[126:127]
	v_cvt_pk_bf16_f32 v114, v114, v115
	v_cvt_pk_bf16_f32 v115, v122, v123
	v_cvt_pk_bf16_f32 v116, v116, v117
	v_lshl_add_u64 v[122:123], s[12:13], 0, v[112:113]
	v_cvt_pk_bf16_f32 v117, v120, v121
	global_store_dwordx4 v[118:119], v[114:117], off offset:256
	global_load_dwordx4 v[216:219], v[180:181], off offset:256
	global_load_dwordx4 v[220:223], v[196:197], off offset:256
	v_add_f32_e32 v124, 1.0, v104
	v_add_f32_e32 v125, 1.0, v105
	v_add_f32_e32 v126, 1.0, v106
	v_add_f32_e32 v127, 1.0, v107
	v_rcp_f32_e32 v104, v108
	v_rcp_f32_e32 v106, v124
	v_rcp_f32_e32 v105, v109
	v_rcp_f32_e32 v107, v125
	v_rcp_f32_e32 v108, v110
	v_rcp_f32_e32 v110, v126
	v_rcp_f32_e32 v109, v111
	v_rcp_f32_e32 v111, v127
	v_exp_f32_e32 v74, v74
	v_exp_f32_e32 v79, v79
	v_exp_f32_e32 v75, v75
	v_add_f32_e32 v76, 1.0, v76
	v_add_f32_e32 v77, 1.0, v77
	v_add_f32_e32 v78, 1.0, v78
	v_add_f32_e32 v79, 1.0, v79
	v_mul_f32_e32 v68, 0xbfb8aa3b, v68
	v_mul_f32_e32 v64, 0xbfb8aa3b, v64
	v_mul_f32_e32 v69, 0xbfb8aa3b, v69
	v_mul_f32_e32 v65, 0xbfb8aa3b, v65
	v_mul_f32_e32 v70, 0xbfb8aa3b, v70
	v_mul_f32_e32 v71, 0xbfb8aa3b, v71
	v_mul_f32_e32 v66, 0xbfb8aa3b, v66
	v_mul_f32_e32 v67, 0xbfb8aa3b, v67
	v_exp_f32_e32 v68, v68
	v_exp_f32_e32 v64, v64
	v_exp_f32_e32 v69, v69
	v_exp_f32_e32 v65, v65
	v_exp_f32_e32 v70, v70
	v_exp_f32_e32 v71, v71
	v_exp_f32_e32 v66, v66
	v_exp_f32_e32 v67, v67
	v_add_f32_e32 v68, 1.0, v68
	v_add_f32_e32 v69, 1.0, v69
	v_mul_f32_e32 v60, 0xbfb8aa3b, v60
	v_mul_f32_e32 v56, 0xbfb8aa3b, v56
	v_mul_f32_e32 v61, 0xbfb8aa3b, v61
	v_mul_f32_e32 v57, 0xbfb8aa3b, v57
	v_mul_f32_e32 v62, 0xbfb8aa3b, v62
	v_mul_f32_e32 v58, 0xbfb8aa3b, v58
	v_mul_f32_e32 v63, 0xbfb8aa3b, v63
	v_mul_f32_e32 v59, 0xbfb8aa3b, v59
	v_exp_f32_e32 v60, v60
	v_exp_f32_e32 v56, v56
	v_exp_f32_e32 v61, v61
	v_exp_f32_e32 v57, v57
	v_exp_f32_e32 v62, v62
	v_exp_f32_e32 v58, v58
	v_exp_f32_e32 v63, v63
	v_exp_f32_e32 v59, v59
	v_add_f32_e32 v60, 1.0, v60
	v_add_f32_e32 v61, 1.0, v61
	v_add_f32_e32 v62, 1.0, v62
	v_add_f32_e32 v63, 1.0, v63
	v_mul_f32_e32 v52, 0xbfb8aa3b, v52
	v_mul_f32_e32 v48, 0xbfb8aa3b, v48
	v_mul_f32_e32 v53, 0xbfb8aa3b, v53
	v_mul_f32_e32 v49, 0xbfb8aa3b, v49
	v_mul_f32_e32 v54, 0xbfb8aa3b, v54
	v_mul_f32_e32 v55, 0xbfb8aa3b, v55
	v_mul_f32_e32 v50, 0xbfb8aa3b, v50
	v_mul_f32_e32 v51, 0xbfb8aa3b, v51
	v_exp_f32_e32 v52, v52
	v_exp_f32_e32 v48, v48
	v_exp_f32_e32 v53, v53
	v_exp_f32_e32 v49, v49
	v_exp_f32_e32 v54, v54
	v_exp_f32_e32 v55, v55
	v_exp_f32_e32 v50, v50
	v_exp_f32_e32 v51, v51
	v_add_f32_e32 v52, 1.0, v52
	v_add_f32_e32 v53, 1.0, v53
	v_mul_f32_e32 v44, 0xbfb8aa3b, v44
	v_mul_f32_e32 v40, 0xbfb8aa3b, v40
	v_mul_f32_e32 v45, 0xbfb8aa3b, v45
	s_waitcnt vmcnt(8)
; __device__ __forceinline__ float fsigmoid(float x) { return __builtin_amdgcn_rcpf(1.0f + __expf(-x)); }
; __device__ __forceinline__ u32x4 pack8(const f32x4 a, const f32x4 b) { u32x4 w; w.x = cvt_pk_bf16(a[0], a[1]); w.y = cvt_pk_bf16(a[2], a[3]); w.z = cvt_pk_bf16(b[0], b[1]); w.w = cvt_pk_bf16(b[2], b[3]); return w; }
; __device__ __forceinline__ void unpack8(const u32x4 w, f32x4& a, f32x4& b) { a = (f32x4){bflo(w.x), bfhi(w.x), bflo(w.y), bfhi(w.y)}; b = (f32x4){bflo(w.z), bfhi(w.z), bflo(w.w), bfhi(w.w)}; }
;     __device__ __forceinline__ void operator()(const f32x4 (&acc)[2][2][4][2], const Unit& u, int wr, int wc, int fr, int fq) const {
;     ...
;             for (int m = 0; m < 4; ++m) { const size_t off = (size_t)(row0 + ai * HALF + m * 16) * 1024 + col0;
; #pragma unroll
;                 for (int bj = 0; bj < 2; ++bj) { f32x4 h0, h1, p0, p1;
;                     unpack8(*(const u32x4*)(hpre + off + bj * HALF), h0, h1); unpack8(*(const u32x4*)(pp + off + bj * HALF), p0, p1);
;                     f32x4 g0, g1;
; #pragma unroll
;                     for (int e = 0; e < 4; ++e) { g0[e] = fsigmoid(acc[ai][bj][m][0][e]); g1[e] = fsigmoid(acc[ai][bj][m][1][e]); }
;                     const f32x4 o0 = h0 + g0 * p0, o1 = h1 + g1 * p1;
;                     if (F32OUT) { *(f32x4*)((float*)O + off + bj * HALF) = o0; *(f32x4*)((float*)O + off + bj * HALF + 4) = o1; }
;                     else *(u32x4*)((bf16_t*)O + off + bj * HALF) = pack8(o0, o1); } }
	v_lshlrev_b32_e32 v124, 16, v224
	v_and_b32_e32 v125, 0xffff0000, v224
	v_lshlrev_b32_e32 v114, 16, v225
	v_and_b32_e32 v115, 0xffff0000, v225
	v_lshlrev_b32_e32 v126, 16, v226
	v_and_b32_e32 v127, 0xffff0000, v226
	v_lshlrev_b32_e32 v116, 16, v227
	v_and_b32_e32 v117, 0xffff0000, v227
	v_lshlrev_b32_e32 v156, 16, v228
	v_and_b32_e32 v157, 0xffff0000, v228
	v_lshlrev_b32_e32 v118, 16, v229
	v_and_b32_e32 v119, 0xffff0000, v229
	v_lshlrev_b32_e32 v158, 16, v230
	v_and_b32_e32 v159, 0xffff0000, v230
	v_lshlrev_b32_e32 v120, 16, v231
	v_and_b32_e32 v121, 0xffff0000, v231
	v_pk_fma_f32 v[108:109], v[108:109], v[118:119], v[114:115]
	v_pk_fma_f32 v[104:105], v[104:105], v[156:157], v[124:125]
	v_pk_fma_f32 v[110:111], v[110:111], v[120:121], v[116:117]
	v_pk_fma_f32 v[106:107], v[106:107], v[158:159], v[126:127]
	v_cvt_pk_bf16_f32 v104, v104, v105
	v_cvt_pk_bf16_f32 v105, v108, v109
	v_exp_f32_e32 v118, v96
	v_cvt_pk_bf16_f32 v106, v106, v107
	v_cvt_pk_bf16_f32 v107, v110, v111
	v_exp_f32_e32 v119, v97
	v_add_f32_e32 v118, 1.0, v118
	v_add_f32_e32 v120, 1.0, v102
	v_add_f32_e32 v122, 1.0, v103
	v_add_f32_e32 v119, 1.0, v119
	v_or_b32_e32 v96, 32, v148
	v_add_f32_e32 v121, 1.0, v98
	v_add_f32_e32 v123, 1.0, v99
	v_lshl_add_u64 v[102:103], s[14:15], 0, v[112:113]
	v_rcp_f32_e32 v98, v100
	v_rcp_f32_e32 v100, v118
	v_rcp_f32_e32 v99, v101
	v_rcp_f32_e32 v101, v119
	v_rcp_f32_e32 v112, v120
	v_rcp_f32_e32 v113, v122
	v_ashrrev_i32_e32 v97, 31, v96
	v_rcp_f32_e32 v118, v121
	v_rcp_f32_e32 v119, v123
	v_lshlrev_b64 v[96:97], 10, v[96:97]
	v_lshl_add_u64 v[96:97], v[96:97], 0, v[146:147]
	global_store_dwordx4 v[102:103], v[104:107], off
	global_load_dwordx4 v[224:227], v[182:183], off
	global_load_dwordx4 v[228:231], v[198:199], off
	v_lshlrev_b64 v[96:97], 1, v[96:97]
	v_lshl_add_u64 v[120:121], s[6:7], 0, v[96:97]
	v_mul_f32_e32 v41, 0xbfb8aa3b, v41
	v_mul_f32_e32 v46, 0xbfb8aa3b, v46
	v_mul_f32_e32 v42, 0xbfb8aa3b, v42
	v_mul_f32_e32 v47, 0xbfb8aa3b, v47
	v_mul_f32_e32 v43, 0xbfb8aa3b, v43
	v_exp_f32_e32 v44, v44
	v_exp_f32_e32 v40, v40
	v_exp_f32_e32 v45, v45
	v_exp_f32_e32 v41, v41
	v_exp_f32_e32 v46, v46
	v_exp_f32_e32 v42, v42
	v_exp_f32_e32 v47, v47
	v_exp_f32_e32 v43, v43
	v_add_f32_e32 v44, 1.0, v44
	v_add_f32_e32 v45, 1.0, v45
	v_add_f32_e32 v46, 1.0, v46
	v_add_f32_e32 v47, 1.0, v47
	v_mul_f32_e32 v36, 0xbfb8aa3b, v36
	v_mul_f32_e32 v32, 0xbfb8aa3b, v32
	v_mul_f32_e32 v37, 0xbfb8aa3b, v37
	v_mul_f32_e32 v33, 0xbfb8aa3b, v33
	v_mul_f32_e32 v38, 0xbfb8aa3b, v38
	v_mul_f32_e32 v39, 0xbfb8aa3b, v39
	v_mul_f32_e32 v34, 0xbfb8aa3b, v34
	v_mul_f32_e32 v35, 0xbfb8aa3b, v35
	v_exp_f32_e32 v36, v36
	v_exp_f32_e32 v32, v32
	v_exp_f32_e32 v37, v37
	v_exp_f32_e32 v33, v33
	v_exp_f32_e32 v38, v38
	v_exp_f32_e32 v39, v39
	v_exp_f32_e32 v34, v34
	v_exp_f32_e32 v35, v35
	v_add_f32_e32 v36, 1.0, v36
	v_add_f32_e32 v37, 1.0, v37
	v_mul_f32_e32 v28, 0xbfb8aa3b, v28
	v_mul_f32_e32 v24, 0xbfb8aa3b, v24
	v_mul_f32_e32 v29, 0xbfb8aa3b, v29
	v_mul_f32_e32 v25, 0xbfb8aa3b, v25
	v_mul_f32_e32 v30, 0xbfb8aa3b, v30
	v_mul_f32_e32 v26, 0xbfb8aa3b, v26
	v_mul_f32_e32 v31, 0xbfb8aa3b, v31
	v_mul_f32_e32 v27, 0xbfb8aa3b, v27
	v_exp_f32_e32 v28, v28
	v_exp_f32_e32 v24, v24
	v_exp_f32_e32 v29, v29
	v_exp_f32_e32 v25, v25
	v_exp_f32_e32 v30, v30
	v_exp_f32_e32 v26, v26
	v_exp_f32_e32 v31, v31
	v_exp_f32_e32 v27, v27
	v_add_f32_e32 v28, 1.0, v28
	v_add_f32_e32 v29, 1.0, v29
	v_add_f32_e32 v30, 1.0, v30
	v_add_f32_e32 v31, 1.0, v31
	s_waitcnt vmcnt(9)
	v_lshlrev_b32_e32 v104, 16, v232
	v_and_b32_e32 v105, 0xffff0000, v232
	v_lshlrev_b32_e32 v106, 16, v233
	v_and_b32_e32 v107, 0xffff0000, v233
	v_lshlrev_b32_e32 v108, 16, v234
	v_and_b32_e32 v109, 0xffff0000, v234
	v_lshlrev_b32_e32 v122, 16, v236
	v_and_b32_e32 v123, 0xffff0000, v236
	v_lshlrev_b32_e32 v114, 16, v237
	v_and_b32_e32 v115, 0xffff0000, v237
	v_lshlrev_b32_e32 v124, 16, v238
	v_and_b32_e32 v125, 0xffff0000, v238
	v_lshlrev_b32_e32 v110, 16, v235
	v_and_b32_e32 v111, 0xffff0000, v235
	v_lshlrev_b32_e32 v116, 16, v239
	v_and_b32_e32 v117, 0xffff0000, v239
	v_pk_fma_f32 v[106:107], v[112:113], v[114:115], v[106:107]
	v_pk_fma_f32 v[98:99], v[98:99], v[122:123], v[104:105]
	v_pk_fma_f32 v[100:101], v[100:101], v[124:125], v[108:109]
	v_pk_fma_f32 v[104:105], v[118:119], v[116:117], v[110:111]
	v_cvt_pk_bf16_f32 v98, v98, v99
	v_cvt_pk_bf16_f32 v99, v106, v107
	v_cvt_pk_bf16_f32 v100, v100, v101
	v_lshl_add_u64 v[106:107], s[12:13], 0, v[96:97]
	v_cvt_pk_bf16_f32 v101, v104, v105
	global_store_dwordx4 v[102:103], v[98:101], off offset:256
	global_load_dwordx4 v[232:235], v[182:183], off offset:256
	global_load_dwordx4 v[236:239], v[198:199], off offset:256
	v_add_f32_e32 v108, 1.0, v88
	v_add_f32_e32 v109, 1.0, v89
	v_add_f32_e32 v110, 1.0, v90
	v_add_f32_e32 v111, 1.0, v91
	v_rcp_f32_e32 v88, v92
	v_rcp_f32_e32 v90, v108
	v_rcp_f32_e32 v89, v93
	v_rcp_f32_e32 v91, v109
	v_rcp_f32_e32 v92, v94
	v_rcp_f32_e32 v94, v110
	v_rcp_f32_e32 v93, v95
	v_rcp_f32_e32 v95, v111
	v_mul_f32_e32 v20, 0xbfb8aa3b, v20
	v_mul_f32_e32 v16, 0xbfb8aa3b, v16
	v_mul_f32_e32 v21, 0xbfb8aa3b, v21
	v_mul_f32_e32 v17, 0xbfb8aa3b, v17
	v_mul_f32_e32 v22, 0xbfb8aa3b, v22
	v_mul_f32_e32 v23, 0xbfb8aa3b, v23
	v_mul_f32_e32 v18, 0xbfb8aa3b, v18
	v_mul_f32_e32 v19, 0xbfb8aa3b, v19
	v_exp_f32_e32 v20, v20
	v_exp_f32_e32 v16, v16
	v_exp_f32_e32 v21, v21
	v_exp_f32_e32 v17, v17
	v_exp_f32_e32 v22, v22
	v_exp_f32_e32 v23, v23
	v_exp_f32_e32 v18, v18
	v_exp_f32_e32 v19, v19
	v_add_f32_e32 v20, 1.0, v20
	v_add_f32_e32 v21, 1.0, v21
	v_mul_f32_e32 v12, 0xbfb8aa3b, v12
	v_mul_f32_e32 v8, 0xbfb8aa3b, v8
	v_mul_f32_e32 v13, 0xbfb8aa3b, v13
	v_mul_f32_e32 v9, 0xbfb8aa3b, v9
	v_mul_f32_e32 v14, 0xbfb8aa3b, v14
	v_mul_f32_e32 v10, 0xbfb8aa3b, v10
	v_mul_f32_e32 v15, 0xbfb8aa3b, v15
	v_mul_f32_e32 v11, 0xbfb8aa3b, v11
	v_exp_f32_e32 v12, v12
	v_exp_f32_e32 v8, v8
	v_exp_f32_e32 v13, v13
	v_exp_f32_e32 v9, v9
	v_exp_f32_e32 v14, v14
	v_exp_f32_e32 v10, v10
	v_exp_f32_e32 v15, v15
	v_exp_f32_e32 v11, v11
	v_add_f32_e32 v12, 1.0, v12
	v_add_f32_e32 v13, 1.0, v13
	v_add_f32_e32 v14, 1.0, v14
	v_add_f32_e32 v15, 1.0, v15
	v_mul_f32_e32 v4, 0xbfb8aa3b, v4
	v_mul_f32_e32 v0, 0xbfb8aa3b, v0
	v_mul_f32_e32 v5, 0xbfb8aa3b, v5
	v_mul_f32_e32 v1, 0xbfb8aa3b, v1
	v_mul_f32_e32 v6, 0xbfb8aa3b, v6
	v_mul_f32_e32 v2, 0xbfb8aa3b, v2
	v_mul_f32_e32 v7, 0xbfb8aa3b, v7
	v_mul_f32_e32 v3, 0xbfb8aa3b, v3
	v_exp_f32_e32 v4, v4
	v_exp_f32_e32 v0, v0
	v_exp_f32_e32 v5, v5
	v_exp_f32_e32 v1, v1
	v_exp_f32_e32 v6, v6
	v_exp_f32_e32 v2, v2
	v_exp_f32_e32 v7, v7
	v_exp_f32_e32 v3, v3
	v_add_f32_e32 v6, 1.0, v6
	v_rcp_f32_e32 v6, v6
	v_add_f32_e32 v7, 1.0, v7
	v_rcp_f32_e32 v7, v7
	s_andn2_b64 vcc, exec, s[2:3]
	s_mov_b64 s[0:1], -1
	s_waitcnt vmcnt(9)
; __device__ __forceinline__ float fsigmoid(float x) { return __builtin_amdgcn_rcpf(1.0f + __expf(-x)); }
; __device__ __forceinline__ u32x4 pack8(const f32x4 a, const f32x4 b) { u32x4 w; w.x = cvt_pk_bf16(a[0], a[1]); w.y = cvt_pk_bf16(a[2], a[3]); w.z = cvt_pk_bf16(b[0], b[1]); w.w = cvt_pk_bf16(b[2], b[3]); return w; }
; __device__ __forceinline__ void unpack8(const u32x4 w, f32x4& a, f32x4& b) { a = (f32x4){bflo(w.x), bfhi(w.x), bflo(w.y), bfhi(w.y)}; b = (f32x4){bflo(w.z), bfhi(w.z), bflo(w.w), bfhi(w.w)}; }
;     __device__ __forceinline__ void operator()(const f32x4 (&acc)[2][2][4][2], const Unit& u, int wr, int wc, int fr, int fq) const {
;     ...
;             for (int m = 0; m < 4; ++m) { const size_t off = (size_t)(row0 + ai * HALF + m * 16) * 1024 + col0;
; #pragma unroll
;                 for (int bj = 0; bj < 2; ++bj) { f32x4 h0, h1, p0, p1;
;                     unpack8(*(const u32x4*)(hpre + off + bj * HALF), h0, h1); unpack8(*(const u32x4*)(pp + off + bj * HALF), p0, p1);
;                     f32x4 g0, g1;
; #pragma unroll
;                     for (int e = 0; e < 4; ++e) { g0[e] = fsigmoid(acc[ai][bj][m][0][e]); g1[e] = fsigmoid(acc[ai][bj][m][1][e]); }
;                     const f32x4 o0 = h0 + g0 * p0, o1 = h1 + g1 * p1;
;                     if (F32OUT) { *(f32x4*)((float*)O + off + bj * HALF) = o0; *(f32x4*)((float*)O + off + bj * HALF + 4) = o1; }
;                     else *(u32x4*)((bf16_t*)O + off + bj * HALF) = pack8(o0, o1); } }
	v_lshlrev_b32_e32 v108, 16, v208
	v_and_b32_e32 v109, 0xffff0000, v208
	v_lshlrev_b32_e32 v98, 16, v209
	v_and_b32_e32 v99, 0xffff0000, v209
	v_lshlrev_b32_e32 v110, 16, v210
	v_and_b32_e32 v111, 0xffff0000, v210
	v_lshlrev_b32_e32 v100, 16, v211
	v_and_b32_e32 v101, 0xffff0000, v211
	v_lshlrev_b32_e32 v112, 16, v212
	v_and_b32_e32 v113, 0xffff0000, v212
	v_lshlrev_b32_e32 v102, 16, v213
	v_and_b32_e32 v103, 0xffff0000, v213
	v_lshlrev_b32_e32 v114, 16, v214
	v_and_b32_e32 v115, 0xffff0000, v214
	v_lshlrev_b32_e32 v104, 16, v215
	v_and_b32_e32 v105, 0xffff0000, v215
	v_pk_fma_f32 v[92:93], v[92:93], v[102:103], v[98:99]
	v_pk_fma_f32 v[88:89], v[88:89], v[112:113], v[108:109]
	v_pk_fma_f32 v[94:95], v[94:95], v[104:105], v[100:101]
	v_pk_fma_f32 v[90:91], v[90:91], v[114:115], v[110:111]
	v_cvt_pk_bf16_f32 v88, v88, v89
	v_cvt_pk_bf16_f32 v89, v92, v93
	v_exp_f32_e32 v102, v80
	v_cvt_pk_bf16_f32 v90, v90, v91
	v_cvt_pk_bf16_f32 v91, v94, v95
	v_exp_f32_e32 v103, v81
	v_add_f32_e32 v102, 1.0, v102
	v_add_f32_e32 v104, 1.0, v86
	v_add_f32_e32 v106, 1.0, v87
	v_add_f32_e32 v103, 1.0, v103
	v_or_b32_e32 v80, 48, v148
	v_add_f32_e32 v105, 1.0, v82
	v_add_f32_e32 v107, 1.0, v83
	v_lshl_add_u64 v[86:87], s[14:15], 0, v[96:97]
	v_rcp_f32_e32 v82, v84
	v_rcp_f32_e32 v84, v102
	v_rcp_f32_e32 v83, v85
	v_rcp_f32_e32 v85, v103
	v_rcp_f32_e32 v96, v104
	v_rcp_f32_e32 v97, v106
	v_ashrrev_i32_e32 v81, 31, v80
	v_rcp_f32_e32 v102, v105
	v_rcp_f32_e32 v103, v107
	v_lshlrev_b64 v[80:81], 10, v[80:81]
	v_lshl_add_u64 v[80:81], v[80:81], 0, v[146:147]
	global_store_dwordx4 v[86:87], v[88:91], off
	global_load_dwordx4 v[208:211], v[184:185], off
	global_load_dwordx4 v[212:215], v[200:201], off
	v_lshlrev_b64 v[80:81], 1, v[80:81]
	v_lshl_add_u64 v[104:105], s[6:7], 0, v[80:81]
	s_waitcnt vmcnt(9)
	v_lshlrev_b32_e32 v88, 16, v216
	v_and_b32_e32 v89, 0xffff0000, v216
	v_lshlrev_b32_e32 v90, 16, v217
	v_and_b32_e32 v91, 0xffff0000, v217
	v_lshlrev_b32_e32 v92, 16, v218
	v_and_b32_e32 v93, 0xffff0000, v218
	v_lshlrev_b32_e32 v106, 16, v220
	v_and_b32_e32 v107, 0xffff0000, v220
	v_lshlrev_b32_e32 v98, 16, v221
	v_and_b32_e32 v99, 0xffff0000, v221
	v_lshlrev_b32_e32 v108, 16, v222
	v_and_b32_e32 v109, 0xffff0000, v222
	v_lshlrev_b32_e32 v94, 16, v219
	v_and_b32_e32 v95, 0xffff0000, v219
	v_lshlrev_b32_e32 v100, 16, v223
	v_and_b32_e32 v101, 0xffff0000, v223
	v_pk_fma_f32 v[90:91], v[96:97], v[98:99], v[90:91]
	v_pk_fma_f32 v[82:83], v[82:83], v[106:107], v[88:89]
	v_pk_fma_f32 v[84:85], v[84:85], v[108:109], v[92:93]
	v_pk_fma_f32 v[88:89], v[102:103], v[100:101], v[94:95]
	v_cvt_pk_bf16_f32 v82, v82, v83
	v_cvt_pk_bf16_f32 v83, v90, v91
	v_cvt_pk_bf16_f32 v84, v84, v85
	v_lshl_add_u64 v[90:91], s[12:13], 0, v[80:81]
	v_cvt_pk_bf16_f32 v85, v88, v89
	global_store_dwordx4 v[86:87], v[82:85], off offset:256
	global_load_dwordx4 v[216:219], v[184:185], off offset:256
	global_load_dwordx4 v[220:223], v[200:201], off offset:256
	v_add_f32_e32 v92, 1.0, v72
	v_add_f32_e32 v93, 1.0, v73
	v_add_f32_e32 v94, 1.0, v74
	v_add_f32_e32 v95, 1.0, v75
	v_rcp_f32_e32 v72, v76
	v_rcp_f32_e32 v74, v92
	v_rcp_f32_e32 v73, v77
	v_rcp_f32_e32 v75, v93
	v_rcp_f32_e32 v76, v78
	v_rcp_f32_e32 v78, v94
	v_rcp_f32_e32 v77, v79
	v_rcp_f32_e32 v79, v95
	s_waitcnt vmcnt(9)
	v_lshlrev_b32_e32 v92, 16, v224
	v_and_b32_e32 v93, 0xffff0000, v224
	v_lshlrev_b32_e32 v82, 16, v225
	v_and_b32_e32 v83, 0xffff0000, v225
	v_lshlrev_b32_e32 v94, 16, v226
	v_and_b32_e32 v95, 0xffff0000, v226
	v_lshlrev_b32_e32 v84, 16, v227
	v_and_b32_e32 v85, 0xffff0000, v227
	v_lshlrev_b32_e32 v96, 16, v228
	v_and_b32_e32 v97, 0xffff0000, v228
	v_lshlrev_b32_e32 v86, 16, v229
	v_and_b32_e32 v87, 0xffff0000, v229
	v_lshlrev_b32_e32 v98, 16, v230
	v_and_b32_e32 v99, 0xffff0000, v230
	v_lshlrev_b32_e32 v88, 16, v231
	v_and_b32_e32 v89, 0xffff0000, v231
	v_pk_fma_f32 v[76:77], v[76:77], v[86:87], v[82:83]
	v_pk_fma_f32 v[72:73], v[72:73], v[96:97], v[92:93]
	v_pk_fma_f32 v[78:79], v[78:79], v[88:89], v[84:85]
	v_pk_fma_f32 v[74:75], v[74:75], v[98:99], v[94:95]
	v_cvt_pk_bf16_f32 v72, v72, v73
	v_cvt_pk_bf16_f32 v73, v76, v77
	v_add_f32_e32 v86, 1.0, v64
	v_cvt_pk_bf16_f32 v74, v74, v75
	v_cvt_pk_bf16_f32 v75, v78, v79
	v_add_f32_e32 v87, 1.0, v65
	v_add_f32_e32 v88, 1.0, v70
	v_add_f32_e32 v90, 1.0, v71
	v_add_f32_e32 v89, 1.0, v66
	v_add_f32_e32 v91, 1.0, v67
	v_lshl_add_u64 v[70:71], s[14:15], 0, v[80:81]
	v_rcp_f32_e32 v66, v68
	v_rcp_f32_e32 v68, v86
	v_rcp_f32_e32 v67, v69
	v_rcp_f32_e32 v69, v87
	v_rcp_f32_e32 v80, v88
	v_rcp_f32_e32 v81, v90
	v_rcp_f32_e32 v86, v89
	v_rcp_f32_e32 v87, v91
	global_store_dwordx4 v[70:71], v[72:75], off
	global_load_dwordx4 v[224:227], v[186:187], off
	global_load_dwordx4 v[228:231], v[202:203], off
	v_lshl_add_u64 v[64:65], v[144:145], 0, s[8:9]
	v_lshl_add_u64 v[88:89], s[6:7], 0, v[64:65]
	s_waitcnt vmcnt(9)
	v_lshlrev_b32_e32 v72, 16, v232
	v_and_b32_e32 v73, 0xffff0000, v232
	v_lshlrev_b32_e32 v74, 16, v233
	v_and_b32_e32 v75, 0xffff0000, v233
	v_lshlrev_b32_e32 v76, 16, v234
	v_and_b32_e32 v77, 0xffff0000, v234
	v_lshlrev_b32_e32 v90, 16, v236
	v_and_b32_e32 v91, 0xffff0000, v236
	v_lshlrev_b32_e32 v82, 16, v237
	v_and_b32_e32 v83, 0xffff0000, v237
	v_lshlrev_b32_e32 v92, 16, v238
	v_and_b32_e32 v93, 0xffff0000, v238
	v_lshlrev_b32_e32 v78, 16, v235
	v_and_b32_e32 v79, 0xffff0000, v235
	v_lshlrev_b32_e32 v84, 16, v239
	v_and_b32_e32 v85, 0xffff0000, v239
	v_pk_fma_f32 v[74:75], v[80:81], v[82:83], v[74:75]
	v_pk_fma_f32 v[66:67], v[66:67], v[90:91], v[72:73]
	v_pk_fma_f32 v[68:69], v[68:69], v[92:93], v[76:77]
	v_pk_fma_f32 v[72:73], v[86:87], v[84:85], v[78:79]
	v_cvt_pk_bf16_f32 v66, v66, v67
	v_cvt_pk_bf16_f32 v67, v74, v75
	v_cvt_pk_bf16_f32 v68, v68, v69
	v_lshl_add_u64 v[74:75], s[12:13], 0, v[64:65]
	v_cvt_pk_bf16_f32 v69, v72, v73
	global_store_dwordx4 v[70:71], v[66:69], off offset:256
	global_load_dwordx4 v[232:235], v[186:187], off offset:256
	global_load_dwordx4 v[236:239], v[202:203], off offset:256
	v_add_f32_e32 v76, 1.0, v56
	v_add_f32_e32 v77, 1.0, v57
	v_add_f32_e32 v78, 1.0, v58
	v_add_f32_e32 v79, 1.0, v59
	v_rcp_f32_e32 v56, v60
	v_rcp_f32_e32 v58, v76
	v_rcp_f32_e32 v57, v61
	v_rcp_f32_e32 v59, v77
	v_rcp_f32_e32 v60, v62
	v_rcp_f32_e32 v62, v78
	v_rcp_f32_e32 v61, v63
	v_rcp_f32_e32 v63, v79
	s_waitcnt vmcnt(9)
; __device__ __forceinline__ float fsigmoid(float x) { return __builtin_amdgcn_rcpf(1.0f + __expf(-x)); }
; __device__ __forceinline__ u32x4 pack8(const f32x4 a, const f32x4 b) { u32x4 w; w.x = cvt_pk_bf16(a[0], a[1]); w.y = cvt_pk_bf16(a[2], a[3]); w.z = cvt_pk_bf16(b[0], b[1]); w.w = cvt_pk_bf16(b[2], b[3]); return w; }
; __device__ __forceinline__ void unpack8(const u32x4 w, f32x4& a, f32x4& b) { a = (f32x4){bflo(w.x), bfhi(w.x), bflo(w.y), bfhi(w.y)}; b = (f32x4){bflo(w.z), bfhi(w.z), bflo(w.w), bfhi(w.w)}; }
;     __device__ __forceinline__ void operator()(const f32x4 (&acc)[2][2][4][2], const Unit& u, int wr, int wc, int fr, int fq) const {
;     ...
;             for (int m = 0; m < 4; ++m) { const size_t off = (size_t)(row0 + ai * HALF + m * 16) * 1024 + col0;
; #pragma unroll
;                 for (int bj = 0; bj < 2; ++bj) { f32x4 h0, h1, p0, p1;
;                     unpack8(*(const u32x4*)(hpre + off + bj * HALF), h0, h1); unpack8(*(const u32x4*)(pp + off + bj * HALF), p0, p1);
;                     f32x4 g0, g1;
; #pragma unroll
;                     for (int e = 0; e < 4; ++e) { g0[e] = fsigmoid(acc[ai][bj][m][0][e]); g1[e] = fsigmoid(acc[ai][bj][m][1][e]); }
;                     const f32x4 o0 = h0 + g0 * p0, o1 = h1 + g1 * p1;
;                     if (F32OUT) { *(f32x4*)((float*)O + off + bj * HALF) = o0; *(f32x4*)((float*)O + off + bj * HALF + 4) = o1; }
;                     else *(u32x4*)((bf16_t*)O + off + bj * HALF) = pack8(o0, o1); } }
	v_lshlrev_b32_e32 v76, 16, v208
	v_and_b32_e32 v77, 0xffff0000, v208
	v_lshlrev_b32_e32 v66, 16, v209
	v_and_b32_e32 v67, 0xffff0000, v209
	v_lshlrev_b32_e32 v78, 16, v210
	v_and_b32_e32 v79, 0xffff0000, v210
	v_lshlrev_b32_e32 v68, 16, v211
	v_and_b32_e32 v69, 0xffff0000, v211
	v_lshlrev_b32_e32 v80, 16, v212
	v_and_b32_e32 v81, 0xffff0000, v212
	v_lshlrev_b32_e32 v70, 16, v213
	v_and_b32_e32 v71, 0xffff0000, v213
	v_lshlrev_b32_e32 v82, 16, v214
	v_and_b32_e32 v83, 0xffff0000, v214
	v_lshlrev_b32_e32 v72, 16, v215
	v_and_b32_e32 v73, 0xffff0000, v215
	v_pk_fma_f32 v[60:61], v[60:61], v[70:71], v[66:67]
	v_pk_fma_f32 v[56:57], v[56:57], v[80:81], v[76:77]
	v_pk_fma_f32 v[62:63], v[62:63], v[72:73], v[68:69]
	v_pk_fma_f32 v[58:59], v[58:59], v[82:83], v[78:79]
	v_cvt_pk_bf16_f32 v56, v56, v57
	v_cvt_pk_bf16_f32 v57, v60, v61
	v_add_f32_e32 v70, 1.0, v48
	v_cvt_pk_bf16_f32 v58, v58, v59
	v_cvt_pk_bf16_f32 v59, v62, v63
	v_add_f32_e32 v71, 1.0, v49
	v_add_f32_e32 v72, 1.0, v54
	v_add_f32_e32 v74, 1.0, v55
	v_add_f32_e32 v73, 1.0, v50
	v_add_f32_e32 v75, 1.0, v51
	v_lshl_add_u64 v[54:55], s[14:15], 0, v[64:65]
	v_rcp_f32_e32 v50, v52
	v_rcp_f32_e32 v52, v70
	v_rcp_f32_e32 v51, v53
	v_rcp_f32_e32 v53, v71
	v_rcp_f32_e32 v64, v72
	v_rcp_f32_e32 v65, v74
	v_rcp_f32_e32 v70, v73
	v_rcp_f32_e32 v71, v75
	global_store_dwordx4 v[54:55], v[56:59], off
	global_load_dwordx4 v[208:211], v[188:189], off
	global_load_dwordx4 v[212:215], v[204:205], off
	v_lshl_add_u64 v[48:49], v[144:145], 0, s[20:21]
	v_lshl_add_u64 v[72:73], s[6:7], 0, v[48:49]
	s_waitcnt vmcnt(9)
	v_lshlrev_b32_e32 v56, 16, v216
	v_and_b32_e32 v57, 0xffff0000, v216
	v_lshlrev_b32_e32 v58, 16, v217
	v_and_b32_e32 v59, 0xffff0000, v217
	v_lshlrev_b32_e32 v60, 16, v218
	v_and_b32_e32 v61, 0xffff0000, v218
	v_lshlrev_b32_e32 v74, 16, v220
	v_and_b32_e32 v75, 0xffff0000, v220
	v_lshlrev_b32_e32 v66, 16, v221
	v_and_b32_e32 v67, 0xffff0000, v221
	v_lshlrev_b32_e32 v76, 16, v222
	v_and_b32_e32 v77, 0xffff0000, v222
	v_lshlrev_b32_e32 v62, 16, v219
	v_and_b32_e32 v63, 0xffff0000, v219
	v_lshlrev_b32_e32 v68, 16, v223
	v_and_b32_e32 v69, 0xffff0000, v223
	v_pk_fma_f32 v[58:59], v[64:65], v[66:67], v[58:59]
	v_pk_fma_f32 v[50:51], v[50:51], v[74:75], v[56:57]
	v_pk_fma_f32 v[52:53], v[52:53], v[76:77], v[60:61]
	v_pk_fma_f32 v[56:57], v[70:71], v[68:69], v[62:63]
	v_cvt_pk_bf16_f32 v50, v50, v51
	v_cvt_pk_bf16_f32 v51, v58, v59
	v_cvt_pk_bf16_f32 v52, v52, v53
	v_lshl_add_u64 v[58:59], s[12:13], 0, v[48:49]
	v_cvt_pk_bf16_f32 v53, v56, v57
	global_store_dwordx4 v[54:55], v[50:53], off offset:256
	global_load_dwordx4 v[216:219], v[188:189], off offset:256
	global_load_dwordx4 v[220:223], v[204:205], off offset:256
	v_add_f32_e32 v60, 1.0, v40
	v_add_f32_e32 v61, 1.0, v41
	v_add_f32_e32 v62, 1.0, v42
	v_add_f32_e32 v63, 1.0, v43
	v_rcp_f32_e32 v40, v44
	v_rcp_f32_e32 v42, v60
	v_rcp_f32_e32 v41, v45
	v_rcp_f32_e32 v43, v61
	v_rcp_f32_e32 v44, v46
	v_rcp_f32_e32 v46, v62
	v_rcp_f32_e32 v45, v47
	v_rcp_f32_e32 v47, v63
	s_waitcnt vmcnt(9)
	v_lshlrev_b32_e32 v60, 16, v224
	v_and_b32_e32 v61, 0xffff0000, v224
	v_lshlrev_b32_e32 v50, 16, v225
	v_and_b32_e32 v51, 0xffff0000, v225
	v_lshlrev_b32_e32 v62, 16, v226
	v_and_b32_e32 v63, 0xffff0000, v226
	v_lshlrev_b32_e32 v52, 16, v227
	v_and_b32_e32 v53, 0xffff0000, v227
	v_lshlrev_b32_e32 v64, 16, v228
	v_and_b32_e32 v65, 0xffff0000, v228
	v_lshlrev_b32_e32 v54, 16, v229
	v_and_b32_e32 v55, 0xffff0000, v229
	v_lshlrev_b32_e32 v66, 16, v230
	v_and_b32_e32 v67, 0xffff0000, v230
	v_lshlrev_b32_e32 v56, 16, v231
	v_and_b32_e32 v57, 0xffff0000, v231
	v_pk_fma_f32 v[44:45], v[44:45], v[54:55], v[50:51]
	v_pk_fma_f32 v[40:41], v[40:41], v[64:65], v[60:61]
	v_pk_fma_f32 v[46:47], v[46:47], v[56:57], v[52:53]
	v_pk_fma_f32 v[42:43], v[42:43], v[66:67], v[62:63]
	v_cvt_pk_bf16_f32 v40, v40, v41
	v_cvt_pk_bf16_f32 v41, v44, v45
	v_add_f32_e32 v54, 1.0, v32
	v_cvt_pk_bf16_f32 v42, v42, v43
	v_cvt_pk_bf16_f32 v43, v46, v47
	v_add_f32_e32 v55, 1.0, v33
	v_add_f32_e32 v56, 1.0, v38
	v_add_f32_e32 v58, 1.0, v39
	v_add_f32_e32 v57, 1.0, v34
	v_add_f32_e32 v59, 1.0, v35
	v_lshl_add_u64 v[38:39], s[14:15], 0, v[48:49]
	v_rcp_f32_e32 v34, v36
	v_rcp_f32_e32 v36, v54
	v_rcp_f32_e32 v35, v37
	v_rcp_f32_e32 v37, v55
	v_rcp_f32_e32 v48, v56
	v_rcp_f32_e32 v49, v58
	v_rcp_f32_e32 v54, v57
	v_rcp_f32_e32 v55, v59
	global_store_dwordx4 v[38:39], v[40:43], off
	global_load_dwordx4 v[224:227], v[190:191], off
	global_load_dwordx4 v[228:231], v[206:207], off
	v_lshl_add_u64 v[32:33], v[144:145], 0, s[22:23]
	v_lshl_add_u64 v[56:57], s[6:7], 0, v[32:33]
	s_waitcnt vmcnt(9)
	v_lshlrev_b32_e32 v40, 16, v232
	v_and_b32_e32 v41, 0xffff0000, v232
	v_lshlrev_b32_e32 v42, 16, v233
	v_and_b32_e32 v43, 0xffff0000, v233
	v_lshlrev_b32_e32 v44, 16, v234
	v_and_b32_e32 v45, 0xffff0000, v234
	v_lshlrev_b32_e32 v58, 16, v236
	v_and_b32_e32 v59, 0xffff0000, v236
	v_lshlrev_b32_e32 v50, 16, v237
	v_and_b32_e32 v51, 0xffff0000, v237
	v_lshlrev_b32_e32 v60, 16, v238
	v_and_b32_e32 v61, 0xffff0000, v238
	v_lshlrev_b32_e32 v46, 16, v235
	v_and_b32_e32 v47, 0xffff0000, v235
	v_lshlrev_b32_e32 v52, 16, v239
	v_and_b32_e32 v53, 0xffff0000, v239
	v_pk_fma_f32 v[42:43], v[48:49], v[50:51], v[42:43]
	v_pk_fma_f32 v[34:35], v[34:35], v[58:59], v[40:41]
	v_pk_fma_f32 v[36:37], v[36:37], v[60:61], v[44:45]
	v_pk_fma_f32 v[40:41], v[54:55], v[52:53], v[46:47]
	v_cvt_pk_bf16_f32 v34, v34, v35
	v_cvt_pk_bf16_f32 v35, v42, v43
	v_cvt_pk_bf16_f32 v36, v36, v37
	v_lshl_add_u64 v[42:43], s[12:13], 0, v[32:33]
	v_cvt_pk_bf16_f32 v37, v40, v41
	global_store_dwordx4 v[38:39], v[34:37], off offset:256
	global_load_dwordx4 v[232:235], v[190:191], off offset:256
	global_load_dwordx4 v[236:239], v[206:207], off offset:256
	v_add_f32_e32 v44, 1.0, v24
	v_add_f32_e32 v45, 1.0, v25
	v_add_f32_e32 v46, 1.0, v26
	v_add_f32_e32 v47, 1.0, v27
	v_rcp_f32_e32 v24, v28
	v_rcp_f32_e32 v26, v44
	v_rcp_f32_e32 v25, v29
	v_rcp_f32_e32 v27, v45
	v_rcp_f32_e32 v28, v30
	v_rcp_f32_e32 v30, v46
	v_rcp_f32_e32 v29, v31
	v_rcp_f32_e32 v31, v47
	s_waitcnt vmcnt(9)
; __device__ __forceinline__ float fsigmoid(float x) { return __builtin_amdgcn_rcpf(1.0f + __expf(-x)); }
; __device__ __forceinline__ u32x4 pack8(const f32x4 a, const f32x4 b) { u32x4 w; w.x = cvt_pk_bf16(a[0], a[1]); w.y = cvt_pk_bf16(a[2], a[3]); w.z = cvt_pk_bf16(b[0], b[1]); w.w = cvt_pk_bf16(b[2], b[3]); return w; }
; __device__ __forceinline__ void unpack8(const u32x4 w, f32x4& a, f32x4& b) { a = (f32x4){bflo(w.x), bfhi(w.x), bflo(w.y), bfhi(w.y)}; b = (f32x4){bflo(w.z), bfhi(w.z), bflo(w.w), bfhi(w.w)}; }
;     __device__ __forceinline__ void operator()(const f32x4 (&acc)[2][2][4][2], const Unit& u, int wr, int wc, int fr, int fq) const {
;     ...
;             for (int m = 0; m < 4; ++m) { const size_t off = (size_t)(row0 + ai * HALF + m * 16) * 1024 + col0;
; #pragma unroll
;                 for (int bj = 0; bj < 2; ++bj) { f32x4 h0, h1, p0, p1;
;                     unpack8(*(const u32x4*)(hpre + off + bj * HALF), h0, h1); unpack8(*(const u32x4*)(pp + off + bj * HALF), p0, p1);
;                     f32x4 g0, g1;
; #pragma unroll
;                     for (int e = 0; e < 4; ++e) { g0[e] = fsigmoid(acc[ai][bj][m][0][e]); g1[e] = fsigmoid(acc[ai][bj][m][1][e]); }
;                     const f32x4 o0 = h0 + g0 * p0, o1 = h1 + g1 * p1;
;                     if (F32OUT) { *(f32x4*)((float*)O + off + bj * HALF) = o0; *(f32x4*)((float*)O + off + bj * HALF + 4) = o1; }
;                     else *(u32x4*)((bf16_t*)O + off + bj * HALF) = pack8(o0, o1); } }
;     }
	v_lshlrev_b32_e32 v44, 16, v208
	v_and_b32_e32 v45, 0xffff0000, v208
	v_lshlrev_b32_e32 v34, 16, v209
	v_and_b32_e32 v35, 0xffff0000, v209
	v_lshlrev_b32_e32 v46, 16, v210
	v_and_b32_e32 v47, 0xffff0000, v210
	v_lshlrev_b32_e32 v36, 16, v211
	v_and_b32_e32 v37, 0xffff0000, v211
	v_lshlrev_b32_e32 v48, 16, v212
	v_and_b32_e32 v49, 0xffff0000, v212
	v_lshlrev_b32_e32 v38, 16, v213
	v_and_b32_e32 v39, 0xffff0000, v213
	v_lshlrev_b32_e32 v50, 16, v214
	v_and_b32_e32 v51, 0xffff0000, v214
	v_lshlrev_b32_e32 v40, 16, v215
	v_and_b32_e32 v41, 0xffff0000, v215
	v_pk_fma_f32 v[28:29], v[28:29], v[38:39], v[34:35]
	v_pk_fma_f32 v[24:25], v[24:25], v[48:49], v[44:45]
	v_pk_fma_f32 v[30:31], v[30:31], v[40:41], v[36:37]
	v_pk_fma_f32 v[26:27], v[26:27], v[50:51], v[46:47]
	v_cvt_pk_bf16_f32 v24, v24, v25
	v_cvt_pk_bf16_f32 v25, v28, v29
	v_add_f32_e32 v38, 1.0, v16
	v_cvt_pk_bf16_f32 v26, v26, v27
	v_cvt_pk_bf16_f32 v27, v30, v31
	v_add_f32_e32 v39, 1.0, v17
	v_add_f32_e32 v40, 1.0, v22
	v_add_f32_e32 v42, 1.0, v23
	v_add_f32_e32 v41, 1.0, v18
	v_add_f32_e32 v43, 1.0, v19
	v_lshl_add_u64 v[22:23], s[14:15], 0, v[32:33]
	v_rcp_f32_e32 v18, v20
	v_rcp_f32_e32 v20, v38
	v_rcp_f32_e32 v19, v21
	v_rcp_f32_e32 v21, v39
	v_rcp_f32_e32 v32, v40
	v_rcp_f32_e32 v33, v42
	v_rcp_f32_e32 v38, v41
	v_rcp_f32_e32 v39, v43
	global_store_dwordx4 v[22:23], v[24:27], off
	s_nop 1
	v_lshl_add_u64 v[16:17], v[144:145], 0, s[24:25]
	v_lshl_add_u64 v[40:41], s[6:7], 0, v[16:17]
	s_waitcnt vmcnt(7)
	v_lshlrev_b32_e32 v24, 16, v216
	v_and_b32_e32 v25, 0xffff0000, v216
	v_lshlrev_b32_e32 v26, 16, v217
	v_and_b32_e32 v27, 0xffff0000, v217
	v_lshlrev_b32_e32 v28, 16, v218
	v_and_b32_e32 v29, 0xffff0000, v218
	v_lshlrev_b32_e32 v42, 16, v220
	v_and_b32_e32 v43, 0xffff0000, v220
	v_lshlrev_b32_e32 v34, 16, v221
	v_and_b32_e32 v35, 0xffff0000, v221
	v_lshlrev_b32_e32 v44, 16, v222
	v_and_b32_e32 v45, 0xffff0000, v222
	v_lshlrev_b32_e32 v30, 16, v219
	v_and_b32_e32 v31, 0xffff0000, v219
	v_lshlrev_b32_e32 v36, 16, v223
	v_and_b32_e32 v37, 0xffff0000, v223
	v_pk_fma_f32 v[26:27], v[32:33], v[34:35], v[26:27]
	v_pk_fma_f32 v[18:19], v[18:19], v[42:43], v[24:25]
	v_pk_fma_f32 v[20:21], v[20:21], v[44:45], v[28:29]
	v_pk_fma_f32 v[24:25], v[38:39], v[36:37], v[30:31]
	v_cvt_pk_bf16_f32 v18, v18, v19
	v_cvt_pk_bf16_f32 v19, v26, v27
	v_cvt_pk_bf16_f32 v20, v20, v21
	v_lshl_add_u64 v[26:27], s[12:13], 0, v[16:17]
	v_cvt_pk_bf16_f32 v21, v24, v25
	global_store_dwordx4 v[22:23], v[18:21], off offset:256
	s_nop 1
	v_add_f32_e32 v28, 1.0, v8
	v_add_f32_e32 v29, 1.0, v9
	v_add_f32_e32 v30, 1.0, v10
	v_add_f32_e32 v31, 1.0, v11
	v_rcp_f32_e32 v8, v12
	v_rcp_f32_e32 v10, v28
	v_rcp_f32_e32 v9, v13
	v_rcp_f32_e32 v11, v29
	v_rcp_f32_e32 v12, v14
	v_rcp_f32_e32 v14, v30
	v_rcp_f32_e32 v13, v15
	v_rcp_f32_e32 v15, v31
	s_waitcnt vmcnt(5)
	v_lshlrev_b32_e32 v28, 16, v224
	v_and_b32_e32 v29, 0xffff0000, v224
	v_lshlrev_b32_e32 v18, 16, v225
	v_and_b32_e32 v19, 0xffff0000, v225
	v_lshlrev_b32_e32 v30, 16, v226
	v_and_b32_e32 v31, 0xffff0000, v226
	v_lshlrev_b32_e32 v20, 16, v227
	v_and_b32_e32 v21, 0xffff0000, v227
	v_lshlrev_b32_e32 v32, 16, v228
	v_and_b32_e32 v33, 0xffff0000, v228
	v_lshlrev_b32_e32 v22, 16, v229
	v_and_b32_e32 v23, 0xffff0000, v229
	v_lshlrev_b32_e32 v34, 16, v230
	v_and_b32_e32 v35, 0xffff0000, v230
	v_lshlrev_b32_e32 v24, 16, v231
	v_and_b32_e32 v25, 0xffff0000, v231
	v_pk_fma_f32 v[12:13], v[12:13], v[22:23], v[18:19]
	v_pk_fma_f32 v[8:9], v[8:9], v[32:33], v[28:29]
	v_pk_fma_f32 v[14:15], v[14:15], v[24:25], v[20:21]
	v_pk_fma_f32 v[10:11], v[10:11], v[34:35], v[30:31]
	v_cvt_pk_bf16_f32 v8, v8, v9
	v_cvt_pk_bf16_f32 v9, v12, v13
	v_add_f32_e32 v22, 1.0, v4
	v_cvt_pk_bf16_f32 v10, v10, v11
	v_cvt_pk_bf16_f32 v11, v14, v15
	v_add_f32_e32 v23, 1.0, v0
	v_add_f32_e32 v24, 1.0, v5
	v_add_f32_e32 v25, 1.0, v1
	v_add_f32_e32 v26, 1.0, v2
	v_add_f32_e32 v27, 1.0, v3
	v_rcp_f32_e32 v0, v22
	v_rcp_f32_e32 v2, v23
	v_rcp_f32_e32 v1, v24
	v_rcp_f32_e32 v3, v25
	v_lshl_add_u64 v[4:5], s[14:15], 0, v[16:17]
	v_rcp_f32_e32 v16, v26
	v_rcp_f32_e32 v17, v27
	global_store_dwordx4 v[4:5], v[8:11], off
	s_nop 1
	s_waitcnt vmcnt(3)
	v_lshlrev_b32_e32 v22, 16, v236
	v_lshlrev_b32_e32 v8, 16, v232
	v_and_b32_e32 v9, 0xffff0000, v232
	v_lshlrev_b32_e32 v10, 16, v233
	v_and_b32_e32 v11, 0xffff0000, v233
	v_lshlrev_b32_e32 v12, 16, v234
	v_and_b32_e32 v13, 0xffff0000, v234
	v_and_b32_e32 v23, 0xffff0000, v236
	v_lshlrev_b32_e32 v24, 16, v238
	v_and_b32_e32 v25, 0xffff0000, v238
	v_lshlrev_b32_e32 v14, 16, v235
	v_and_b32_e32 v15, 0xffff0000, v235
	v_lshlrev_b32_e32 v18, 16, v237
	v_and_b32_e32 v19, 0xffff0000, v237
	v_lshlrev_b32_e32 v20, 16, v239
	v_and_b32_e32 v21, 0xffff0000, v239
	v_pk_fma_f32 v[0:1], v[0:1], v[22:23], v[8:9]
	v_pk_fma_f32 v[2:3], v[2:3], v[24:25], v[12:13]
	v_pk_fma_f32 v[6:7], v[6:7], v[18:19], v[10:11]
	v_pk_fma_f32 v[8:9], v[16:17], v[20:21], v[14:15]
	v_cvt_pk_bf16_f32 v0, v0, v1
	v_cvt_pk_bf16_f32 v1, v6, v7
	v_cvt_pk_bf16_f32 v2, v2, v3
	s_nop 0
	v_cvt_pk_bf16_f32 v3, v8, v9
	global_store_dwordx4 v[4:5], v[0:3], off offset:256
	s_nop 1
	s_cbranch_vccnz .LBB0_1167
	s_andn2_b64 vcc, exec, s[10:11]
	s_cbranch_vccnz .LBB0_1166
	s_barrier
	s_branch .LBB0_1166
